# v23: v4 plus QKV projection unit order interleaving light (Q) and heavy (K,V with f32 copies) column tiles so store epilogues desynchronise
# speedup vs baseline: 1.0016x; 1.0013x over previous
.LBB0_1066:
	s_mul_i32 s98, s14, 11
	s_lshr_b32 s98, s98, 5
	s_mul_i32 s99, s98, 3
	s_sub_u32 s99, s14, s99
	s_lshl_b32 s99, s99, 2
	s_add_u32 s14, s99, s98
	s_andn2_b64 vcc, exec, s[0:1]
	s_cbranch_vccnz .LBB0_1165
	s_mov_b64 s[0:1], 0
	s_cmpk_lt_u32 s14, 0x100
	s_mov_b64 s[6:7], 0
	s_cbranch_scc1 .LBB0_1069
	s_ashr_i32 s0, s14, 4
	s_and_b32 s0, s0, -16
	s_ashr_i32 s1, s0, 31
	s_lshl_b64 s[0:1], s[0:1], 7
	s_add_u32 s6, s0, 0xfffff800
	s_addc_u32 s7, s1, -1
	s_movk_i32 s0, 0xf000
	s_mov_b32 s1, -1

.LBB0_1080:
	s_mul_i32 s98, s81, 11
	s_lshr_b32 s98, s98, 5
	s_mul_i32 s99, s98, 3
	s_sub_u32 s99, s81, s99
	s_lshl_b32 s99, s99, 2
	s_add_u32 s81, s99, s98
	s_nop 0
	v_cndmask_b32_e64 v0, 0, 1, s[0:1]
	v_cmp_ne_u32_e64 s[6:7], 1, v0
	s_andn2_b64 vcc, exec, s[0:1]
	s_mov_b64 s[0:1], s[36:37]
	s_cbranch_vccnz .LBB0_1084
	s_cmpk_lt_u32 s81, 0x100
	s_mov_b64 s[0:1], 0
	s_cbranch_scc1 .LBB0_1083
	s_ashr_i32 s0, s81, 4
	s_and_b32 s0, s0, -16
	s_ashr_i32 s1, s0, 31
	s_lshl_b64 s[0:1], s[0:1], 7
	s_add_u32 s0, s0, 0xfffff800
	s_addc_u32 s1, s1, -1
